# v84 plus prologue modulate loop: scale vector resident in registers, shift vector staged in LDS
# speedup vs baseline: 1.0137x; 1.0137x over previous
.LBB0_76:
	s_or_b64 exec, exec, s[8:9]
	v_cndmask_b32_e64 v2, 0, 1, s[4:5]
	s_lshl_b32 s74, s42, 4
	v_cmp_ne_u32_e64 s[8:9], 1, v2
	s_add_u32 s24, s26, 0x100000
	s_addc_u32 s25, s27, 0
	v_writelane_b32 v254, s8, 45
	s_andn2_b64 vcc, exec, s[4:5]
	v_lshlrev_b32_e32 v54, 2, v84
	v_writelane_b32 v254, s9, 46
	s_waitcnt lgkmcnt(0)
	s_barrier
	s_cbranch_vccnz .LBB0_91
	s_add_u32 s28, s26, 0x102000
	s_addc_u32 s29, s27, 0
	s_add_u32 s3, s26, 0xcc1b000
	s_addc_u32 s43, s27, 0
	s_add_u32 s56, s26, 0x15119000
	s_addc_u32 s57, s27, 0
	s_add_u32 s58, s26, 0x1515b000
	s_addc_u32 s59, s27, 0
	s_mov_b32 s40, s70
	s_ashr_i32 s41, s70, 31
	s_lshl_b64 s[8:9], s[40:41], 5
	s_add_u32 s60, s8, 0x15119000
	s_addc_u32 s61, s9, 0
	s_ashr_i32 s75, s74, 31
	s_lshl_b64 s[30:31], s[74:75], 5
	s_lshl_b64 s[8:9], s[40:41], 13
	v_ashrrev_i32_e32 v55, 31, v54
	s_add_u32 s8, s20, s8
	v_lshlrev_b64 v[2:3], 2, v[54:55]
	s_addc_u32 s9, s21, s9
	v_lshl_add_u64 v[56:57], s[20:21], 0, v[2:3]
	v_lshl_add_u64 v[2:3], s[8:9], 0, v[2:3]
	s_mov_b64 s[8:9], 0x1c00
	v_mbcnt_hi_u32_b32 v55, -1, v1
	v_lshl_add_u64 v[58:59], v[2:3], 0, s[8:9]
	v_and_b32_e32 v2, 64, v55
	s_movk_i32 s38, 0xffe0
	s_lshl_b64 s[20:21], s[74:75], 13
	s_lshl_b64 s[34:35], s[40:41], 12
	s_lshl_b64 s[36:37], s[74:75], 12
	s_movk_i32 s62, 0x1000
	s_movk_i32 s63, 0x7fff
	s_mov_b32 s64, 0xffff0000
	s_mov_b32 s65, 0xcc1b000
	v_xor_b32_e32 v85, 32, v55
	v_add_u32_e32 v86, 64, v2
	v_xor_b32_e32 v87, 16, v55
	v_xor_b32_e32 v88, 8, v55
	v_xor_b32_e32 v89, 4, v55
	v_xor_b32_e32 v90, 2, v55
	v_xor_b32_e32 v91, 1, v55
	v_mov_b32_e32 v61, 0
	s_mov_b32 s39, -1
	s_mov_b32 s66, 0xbfb8aa3b
	s_mov_b32 s67, 0x800000
	s_mov_b32 s68, 0x3f317217
	s_mov_b32 s69, 0x7f800000
	v_mov_b32_e32 v92, 0x41b17218
	v_lshlrev_b32_e32 v205, 4, v0
	global_load_dwordx4 v[208:211], v205, s[24:25]
	v_add_u32_e32 v206, 0x20400, v205
	s_waitcnt vmcnt(0)
	ds_write_b128 v206, v[208:211]
	s_waitcnt lgkmcnt(0)
	s_barrier
	v_lshlrev_b32_e32 v207, 4, v232
	v_add_u32_e32 v252, 0x1000, v207
	v_add_u32_e32 v206, 0x20400, v207
	global_load_dwordx4 v[208:211], v207, s[28:29]
	global_load_dwordx4 v[212:215], v207, s[28:29] offset:1024
	global_load_dwordx4 v[216:219], v207, s[28:29] offset:2048
	global_load_dwordx4 v[220:223], v207, s[28:29] offset:3072
	global_load_dwordx4 v[224:227], v252, s[28:29]
	global_load_dwordx4 v[228:231], v252, s[28:29] offset:1024
	global_load_dwordx4 v[236:239], v252, s[28:29] offset:2048
	global_load_dwordx4 v[240:243], v252, s[28:29] offset:3072
	s_waitcnt vmcnt(0)
	s_branch .LBB0_80

.LBB0_80:
	s_add_i32 s8, s72, s40
	s_cmpk_lt_i32 s8, 0x2000
	s_cselect_b32 s48, s8, s40
	v_add_co_u32_e32 v2, vcc, 0xfffff000, v58
	s_ashr_i32 s49, s48, 31
	s_waitcnt lgkmcnt(0)
	v_addc_co_u32_e32 v3, vcc, -1, v59, vcc
	s_lshl_b64 s[8:9], s[48:49], 13
	global_load_dwordx4 v[64:67], v[2:3], off offset:-3072
	global_load_dwordx4 v[68:71], v[2:3], off offset:-2048
	global_load_dwordx4 v[78:81], v[2:3], off offset:-1024
	global_load_dwordx4 v[50:53], v[58:59], off offset:-4096
	global_load_dwordx4 v[46:49], v[58:59], off offset:-3072
	global_load_dwordx4 v[42:45], v[58:59], off offset:-2048
	global_load_dwordx4 v[38:41], v[58:59], off offset:-1024
	global_load_dwordx4 v[34:37], v[58:59], off
	v_lshl_add_u64 v[2:3], v[56:57], 0, s[8:9]
	global_load_dwordx4 v[30:33], v[2:3], off
	global_load_dwordx4 v[26:29], v[2:3], off offset:1024
	global_load_dwordx4 v[22:25], v[2:3], off offset:2048
	global_load_dwordx4 v[18:21], v[2:3], off offset:3072
	v_add_co_u32_e32 v2, vcc, s62, v2
	v_mov_b32_e32 v60, v84
	s_nop 0
	v_addc_co_u32_e32 v3, vcc, 0, v3, vcc
	global_load_dwordx4 v[14:17], v[2:3], off
	global_load_dwordx4 v[10:13], v[2:3], off offset:1024
	global_load_dwordx4 v[6:9], v[2:3], off offset:2048
	s_nop 0
	global_load_dwordx4 v[2:5], v[2:3], off offset:3072
	s_ashr_i32 s41, s40, 31
	v_lshlrev_b32_e32 v62, 2, v60
	v_ashrrev_i32_e32 v63, 31, v62
	v_lshlrev_b64 v[72:73], 2, v[62:63]
	v_lshl_add_u64 v[82:83], s[28:29], 0, v[72:73]
	s_nop 1
	v_mov_b64_e32 v[94:95], v[208:209]
	v_mov_b64_e32 v[96:97], v[210:211]
	v_lshl_add_u64 v[76:77], s[24:25], 0, v[72:73]
	ds_read_b128 v[98:101], v206
	s_add_u32 s8, s26, s34
	s_addc_u32 s9, s27, s35
	v_lshl_add_u64 v[62:63], v[62:63], 1, s[8:9]
	v_add_co_u32_e32 v74, vcc, s65, v62
	s_lshl_b64 s[8:9], s[48:49], 12
	s_nop 0
	v_addc_co_u32_e32 v75, vcc, 0, v63, vcc
	s_add_u32 s8, s3, s8
	s_addc_u32 s9, s43, s9
	v_cmp_lt_i32_e64 s[14:15], v90, v86
	s_nop 0
	v_pk_add_f32 v[62:63], v[96:97], 1.0 op_sel_hi:[1,0]
	v_pk_add_f32 v[72:73], v[94:95], 1.0 op_sel_hi:[1,0]
	s_waitcnt vmcnt(0) lgkmcnt(0)
	v_pk_fma_f32 v[62:63], v[66:67], v[62:63], v[100:101]
	v_pk_fma_f32 v[64:65], v[64:65], v[72:73], v[98:99]
	v_cvt_pk_bf16_f32 v66, v64, v65
	v_cvt_pk_bf16_f32 v67, v62, v63
	global_store_dwordx2 v[74:75], v[66:67], off
	s_nop 1
	v_mov_b64_e32 v[94:95], v[212:213]
	v_mov_b64_e32 v[96:97], v[214:215]
	ds_read_b128 v[98:101], v206 offset:1024
	s_nop 0
	v_pk_add_f32 v[66:67], v[96:97], 1.0 op_sel_hi:[1,0]
	v_pk_add_f32 v[72:73], v[94:95], 1.0 op_sel_hi:[1,0]
	s_waitcnt lgkmcnt(0)
	v_pk_fma_f32 v[66:67], v[70:71], v[66:67], v[100:101]
	v_pk_fma_f32 v[68:69], v[68:69], v[72:73], v[98:99]
	v_cvt_pk_bf16_f32 v70, v68, v69
	v_cvt_pk_bf16_f32 v71, v66, v67
	global_store_dwordx2 v[74:75], v[70:71], off offset:512
	s_nop 1
	v_mov_b64_e32 v[70:71], v[216:217]
	v_mov_b64_e32 v[72:73], v[218:219]
	s_nop 0
	ds_read_b128 v[94:97], v206 offset:2048
	s_nop 0
	v_pk_add_f32 v[72:73], v[72:73], 1.0 op_sel_hi:[1,0]
	v_pk_add_f32 v[98:99], v[70:71], 1.0 op_sel_hi:[1,0]
	s_waitcnt lgkmcnt(0)
	v_pk_fma_f32 v[70:71], v[80:81], v[72:73], v[96:97]
	v_pk_fma_f32 v[72:73], v[78:79], v[98:99], v[94:95]
	v_cvt_pk_bf16_f32 v78, v72, v73
	v_cvt_pk_bf16_f32 v79, v70, v71
	global_store_dwordx2 v[74:75], v[78:79], off offset:1024
	s_nop 1
	v_mov_b64_e32 v[78:79], v[220:221]
	v_mov_b64_e32 v[80:81], v[222:223]
	s_nop 0
	ds_read_b128 v[94:97], v206 offset:3072
	v_add_co_u32_e32 v98, vcc, s62, v82
	s_nop 0
	v_pk_add_f32 v[80:81], v[80:81], 1.0 op_sel_hi:[1,0]
	v_pk_add_f32 v[78:79], v[78:79], 1.0 op_sel_hi:[1,0]
	s_waitcnt lgkmcnt(0)
	v_pk_fma_f32 v[52:53], v[52:53], v[80:81], v[96:97]
	v_pk_fma_f32 v[50:51], v[50:51], v[78:79], v[94:95]
	v_addc_co_u32_e32 v99, vcc, 0, v83, vcc
	v_cvt_pk_bf16_f32 v78, v50, v51
	v_cvt_pk_bf16_f32 v79, v52, v53
	global_store_dwordx2 v[74:75], v[78:79], off offset:1536
	v_add_co_u32_e32 v100, vcc, s62, v76
	s_nop 1
	v_mov_b64_e32 v[78:79], v[224:225]
	v_mov_b64_e32 v[80:81], v[226:227]
	s_nop 0
	v_addc_co_u32_e32 v101, vcc, 0, v77, vcc
	ds_read_b128 v[94:97], v206 offset:4096
	s_nop 0
	v_pk_add_f32 v[76:77], v[80:81], 1.0 op_sel_hi:[1,0]
	v_pk_add_f32 v[78:79], v[78:79], 1.0 op_sel_hi:[1,0]
	s_waitcnt lgkmcnt(0)
	v_pk_fma_f32 v[48:49], v[48:49], v[76:77], v[96:97]
	v_pk_fma_f32 v[46:47], v[46:47], v[78:79], v[94:95]
	v_cvt_pk_bf16_f32 v76, v46, v47
	v_cvt_pk_bf16_f32 v77, v48, v49
	global_store_dwordx2 v[74:75], v[76:77], off offset:2048
	s_nop 1
	v_mov_b64_e32 v[76:77], v[228:229]
	v_mov_b64_e32 v[78:79], v[230:231]
	s_nop 0
	ds_read_b128 v[80:83], v206 offset:5120
	s_nop 0
	v_pk_add_f32 v[78:79], v[78:79], 1.0 op_sel_hi:[1,0]
	v_pk_add_f32 v[76:77], v[76:77], 1.0 op_sel_hi:[1,0]
	s_waitcnt lgkmcnt(0)
	v_pk_fma_f32 v[44:45], v[44:45], v[78:79], v[82:83]
	v_pk_fma_f32 v[42:43], v[42:43], v[76:77], v[80:81]
	v_cvt_pk_bf16_f32 v76, v42, v43
	v_cvt_pk_bf16_f32 v77, v44, v45
	global_store_dwordx2 v[74:75], v[76:77], off offset:2560
	s_nop 1
	v_mov_b64_e32 v[76:77], v[236:237]
	v_mov_b64_e32 v[78:79], v[238:239]
	s_nop 0
	ds_read_b128 v[80:83], v206 offset:6144
	s_nop 0
	v_pk_add_f32 v[78:79], v[78:79], 1.0 op_sel_hi:[1,0]
	v_pk_add_f32 v[76:77], v[76:77], 1.0 op_sel_hi:[1,0]
	s_waitcnt lgkmcnt(0)
	v_pk_fma_f32 v[40:41], v[40:41], v[78:79], v[82:83]
	v_pk_fma_f32 v[38:39], v[38:39], v[76:77], v[80:81]
	v_cvt_pk_bf16_f32 v76, v38, v39
	v_cvt_pk_bf16_f32 v77, v40, v41
	global_store_dwordx2 v[74:75], v[76:77], off offset:3072
	s_nop 1
	v_mov_b64_e32 v[76:77], v[240:241]
	v_mov_b64_e32 v[78:79], v[242:243]
	s_nop 0
	ds_read_b128 v[80:83], v206 offset:7168
	s_nop 0
	v_pk_add_f32 v[78:79], v[78:79], 1.0 op_sel_hi:[1,0]
	v_pk_add_f32 v[76:77], v[76:77], 1.0 op_sel_hi:[1,0]
	s_waitcnt lgkmcnt(0)
	v_pk_fma_f32 v[36:37], v[36:37], v[78:79], v[82:83]
	v_pk_fma_f32 v[34:35], v[34:35], v[76:77], v[80:81]
	v_cvt_pk_bf16_f32 v76, v34, v35
	v_cvt_pk_bf16_f32 v77, v36, v37
	global_store_dwordx2 v[74:75], v[76:77], off offset:3584
	s_nop 0
	v_lshlrev_b32_e32 v80, 2, v60
	v_ashrrev_i32_e32 v81, 31, v80
	v_lshlrev_b64 v[74:75], 2, v[80:81]
	v_lshl_add_u64 v[98:99], s[28:29], 0, v[74:75]
	s_nop 1
	v_mov_b64_e32 v[76:77], v[208:209]
	v_mov_b64_e32 v[78:79], v[210:211]
	v_lshl_add_u64 v[74:75], s[24:25], 0, v[74:75]
	ds_read_b128 v[94:97], v206
	v_lshl_add_u64 v[82:83], v[80:81], 1, s[8:9]
	s_nop 0
	v_pk_add_f32 v[78:79], v[78:79], 1.0 op_sel_hi:[1,0]
	v_pk_add_f32 v[76:77], v[76:77], 1.0 op_sel_hi:[1,0]
	s_waitcnt lgkmcnt(0)
	v_pk_fma_f32 v[32:33], v[32:33], v[78:79], v[96:97]
	v_pk_fma_f32 v[30:31], v[30:31], v[76:77], v[94:95]
	v_cvt_pk_bf16_f32 v76, v30, v31
	v_cvt_pk_bf16_f32 v77, v32, v33
	global_store_dwordx2 v[82:83], v[76:77], off
	s_nop 1
	v_mov_b64_e32 v[76:77], v[212:213]
	v_mov_b64_e32 v[78:79], v[214:215]
	s_nop 0
	ds_read_b128 v[94:97], v206 offset:1024
	s_nop 0
	v_pk_add_f32 v[78:79], v[78:79], 1.0 op_sel_hi:[1,0]
	v_pk_add_f32 v[76:77], v[76:77], 1.0 op_sel_hi:[1,0]
	s_waitcnt lgkmcnt(0)
	v_pk_fma_f32 v[28:29], v[28:29], v[78:79], v[96:97]
	v_pk_fma_f32 v[26:27], v[26:27], v[76:77], v[94:95]
	v_cvt_pk_bf16_f32 v76, v26, v27
	v_cvt_pk_bf16_f32 v77, v28, v29
	global_store_dwordx2 v[82:83], v[76:77], off offset:512
	s_nop 1
	v_mov_b64_e32 v[76:77], v[216:217]
	v_mov_b64_e32 v[78:79], v[218:219]
	s_nop 0
	ds_read_b128 v[94:97], v206 offset:2048
	s_nop 0
	v_pk_add_f32 v[78:79], v[78:79], 1.0 op_sel_hi:[1,0]
	v_pk_add_f32 v[76:77], v[76:77], 1.0 op_sel_hi:[1,0]
	s_waitcnt lgkmcnt(0)
	v_pk_fma_f32 v[24:25], v[24:25], v[78:79], v[96:97]
	v_pk_fma_f32 v[22:23], v[22:23], v[76:77], v[94:95]
	v_cvt_pk_bf16_f32 v76, v22, v23
	v_cvt_pk_bf16_f32 v77, v24, v25
	global_store_dwordx2 v[82:83], v[76:77], off offset:1024
	s_nop 1
	v_mov_b64_e32 v[76:77], v[220:221]
	v_mov_b64_e32 v[78:79], v[222:223]
	s_nop 0
	ds_read_b128 v[94:97], v206 offset:3072
	v_add_co_u32_e32 v98, vcc, s62, v98
	s_nop 0
	v_pk_add_f32 v[78:79], v[78:79], 1.0 op_sel_hi:[1,0]
	v_pk_add_f32 v[76:77], v[76:77], 1.0 op_sel_hi:[1,0]
	s_waitcnt lgkmcnt(0)
	v_pk_fma_f32 v[20:21], v[20:21], v[78:79], v[96:97]
	v_pk_fma_f32 v[18:19], v[18:19], v[76:77], v[94:95]
	v_addc_co_u32_e32 v99, vcc, 0, v99, vcc
	v_cvt_pk_bf16_f32 v76, v18, v19
	v_cvt_pk_bf16_f32 v77, v20, v21
	global_store_dwordx2 v[82:83], v[76:77], off offset:1536
	v_add_co_u32_e32 v100, vcc, s62, v74
	s_nop 1
	v_mov_b64_e32 v[76:77], v[224:225]
	v_mov_b64_e32 v[78:79], v[226:227]
	s_nop 0
	v_addc_co_u32_e32 v101, vcc, 0, v75, vcc
	ds_read_b128 v[94:97], v206 offset:4096
	v_cmp_lt_i32_e32 vcc, v85, v86
	s_nop 0
	v_pk_add_f32 v[74:75], v[78:79], 1.0 op_sel_hi:[1,0]
	v_pk_add_f32 v[76:77], v[76:77], 1.0 op_sel_hi:[1,0]
	v_cndmask_b32_e32 v93, v55, v85, vcc
	s_waitcnt lgkmcnt(0)
	v_pk_fma_f32 v[16:17], v[16:17], v[74:75], v[96:97]
	v_pk_fma_f32 v[14:15], v[14:15], v[76:77], v[94:95]
	v_cvt_pk_bf16_f32 v74, v14, v15
	v_cvt_pk_bf16_f32 v75, v16, v17
	global_store_dwordx2 v[82:83], v[74:75], off offset:2048
	s_nop 1
	v_mov_b64_e32 v[74:75], v[228:229]
	v_mov_b64_e32 v[76:77], v[230:231]
	s_nop 0
	ds_read_b128 v[78:81], v206 offset:5120
	v_cmp_lt_i32_e32 vcc, v87, v86
	s_nop 0
	v_pk_add_f32 v[76:77], v[76:77], 1.0 op_sel_hi:[1,0]
	v_pk_add_f32 v[94:95], v[74:75], 1.0 op_sel_hi:[1,0]
	s_waitcnt lgkmcnt(0)
	v_pk_fma_f32 v[74:75], v[12:13], v[76:77], v[80:81]
	v_pk_fma_f32 v[76:77], v[10:11], v[94:95], v[78:79]
	v_cvt_pk_bf16_f32 v10, v76, v77
	v_cvt_pk_bf16_f32 v11, v74, v75
	global_store_dwordx2 v[82:83], v[10:11], off offset:2560
	s_nop 1
	v_mov_b64_e32 v[10:11], v[236:237]
	v_mov_b64_e32 v[12:13], v[238:239]
	s_nop 0
	ds_read_b128 v[94:97], v206 offset:6144
	s_nop 0
	v_pk_add_f32 v[12:13], v[12:13], 1.0 op_sel_hi:[1,0]
	v_pk_add_f32 v[10:11], v[10:11], 1.0 op_sel_hi:[1,0]
	s_waitcnt lgkmcnt(0)
	v_pk_fma_f32 v[78:79], v[8:9], v[12:13], v[96:97]
	v_pk_fma_f32 v[80:81], v[6:7], v[10:11], v[94:95]
	v_cvt_pk_bf16_f32 v6, v80, v81
	v_cvt_pk_bf16_f32 v7, v78, v79
	global_store_dwordx2 v[82:83], v[6:7], off offset:3072
	s_nop 1
	v_mov_b64_e32 v[10:11], v[240:241]
	v_mov_b64_e32 v[12:13], v[242:243]
	s_nop 0
	ds_read_b128 v[6:9], v206 offset:7168
	v_cndmask_b32_e32 v94, v55, v87, vcc
	v_cmp_lt_i32_e32 vcc, v88, v86
	v_lshlrev_b32_e32 v95, 2, v93
	v_lshlrev_b32_e32 v94, 2, v94
	v_cndmask_b32_e32 v97, v55, v88, vcc
	v_lshlrev_b32_e32 v93, 2, v97
	v_cmp_lt_i32_e32 vcc, v89, v86
	s_nop 0
	v_pk_add_f32 v[12:13], v[12:13], 1.0 op_sel_hi:[1,0]
	v_pk_add_f32 v[10:11], v[10:11], 1.0 op_sel_hi:[1,0]
	s_waitcnt lgkmcnt(0)
	v_pk_fma_f32 v[4:5], v[4:5], v[12:13], v[8:9]
	v_pk_fma_f32 v[2:3], v[2:3], v[10:11], v[6:7]
	v_cvt_pk_bf16_f32 v6, v2, v3
	v_cvt_pk_bf16_f32 v7, v4, v5
	global_store_dwordx2 v[82:83], v[6:7], off offset:3584
	s_load_dwordx2 s[50:51], s[6:7], 0x68
	v_lshl_add_u32 v97, v60, 4, 0
	ds_read_b128 v[6:9], v97
	ds_read_b128 v[10:13], v97 offset:1024
	ds_read_b128 v[140:143], v97 offset:2048
	ds_read_b128 v[144:147], v97 offset:3072
	ds_read_b128 v[148:151], v97 offset:4096
	ds_read_b128 v[152:155], v97 offset:5120
	ds_read_b128 v[156:159], v97 offset:6144
	ds_read_b128 v[160:163], v97 offset:7168
	s_waitcnt lgkmcnt(0)
	v_pk_fma_f32 v[82:83], v[64:65], v[6:7], 0 op_sel_hi:[1,1,0]
	v_pk_fma_f32 v[6:7], v[30:31], v[6:7], 0 op_sel_hi:[1,1,0]
	v_pk_fma_f32 v[82:83], v[62:63], v[8:9], v[82:83]
	v_pk_fma_f32 v[6:7], v[32:33], v[8:9], v[6:7]
	v_pk_fma_f32 v[8:9], v[68:69], v[10:11], v[82:83]
	v_pk_fma_f32 v[6:7], v[26:27], v[10:11], v[6:7]
	v_pk_fma_f32 v[8:9], v[66:67], v[12:13], v[8:9]
	v_pk_fma_f32 v[6:7], v[28:29], v[12:13], v[6:7]
	v_pk_fma_f32 v[8:9], v[72:73], v[140:141], v[8:9]
	v_pk_fma_f32 v[6:7], v[22:23], v[140:141], v[6:7]
	v_pk_fma_f32 v[8:9], v[70:71], v[142:143], v[8:9]
	v_pk_fma_f32 v[6:7], v[24:25], v[142:143], v[6:7]
	v_pk_fma_f32 v[8:9], v[50:51], v[144:145], v[8:9]
	v_pk_fma_f32 v[6:7], v[18:19], v[144:145], v[6:7]
	v_pk_fma_f32 v[8:9], v[52:53], v[146:147], v[8:9]
	v_pk_fma_f32 v[6:7], v[20:21], v[146:147], v[6:7]
	v_pk_fma_f32 v[8:9], v[46:47], v[148:149], v[8:9]
	v_pk_fma_f32 v[6:7], v[14:15], v[148:149], v[6:7]
	v_pk_fma_f32 v[8:9], v[48:49], v[150:151], v[8:9]
	v_pk_fma_f32 v[6:7], v[16:17], v[150:151], v[6:7]
	v_pk_fma_f32 v[8:9], v[42:43], v[152:153], v[8:9]
	v_pk_fma_f32 v[6:7], v[76:77], v[152:153], v[6:7]
	v_pk_fma_f32 v[8:9], v[44:45], v[154:155], v[8:9]
	v_pk_fma_f32 v[6:7], v[74:75], v[154:155], v[6:7]
	v_pk_fma_f32 v[8:9], v[38:39], v[156:157], v[8:9]
	v_pk_fma_f32 v[6:7], v[80:81], v[156:157], v[6:7]
	v_pk_fma_f32 v[8:9], v[40:41], v[158:159], v[8:9]
	v_pk_fma_f32 v[6:7], v[78:79], v[158:159], v[6:7]
	v_pk_fma_f32 v[8:9], v[34:35], v[160:161], v[8:9]
	v_pk_fma_f32 v[6:7], v[2:3], v[160:161], v[6:7]
	v_pk_fma_f32 v[8:9], v[36:37], v[162:163], v[8:9]
	v_pk_fma_f32 v[6:7], v[4:5], v[162:163], v[6:7]
	v_add_f32_e32 v197, v8, v9
	v_add_f32_e32 v6, v6, v7
	ds_read_b128 v[8:11], v97 offset:8192
	ds_read_b128 v[140:143], v97 offset:9216
	ds_read_b128 v[144:147], v97 offset:10240
	ds_read_b128 v[148:151], v97 offset:11264
	ds_read_b128 v[152:155], v97 offset:12288
	ds_read_b128 v[156:159], v97 offset:13312
	ds_read_b128 v[160:163], v97 offset:14336
	ds_read_b128 v[164:167], v97 offset:15360
	s_waitcnt lgkmcnt(7)
	v_pk_fma_f32 v[12:13], v[64:65], v[8:9], 0 op_sel_hi:[1,1,0]
	v_pk_fma_f32 v[8:9], v[30:31], v[8:9], 0 op_sel_hi:[1,1,0]
	v_pk_fma_f32 v[12:13], v[62:63], v[10:11], v[12:13]
	v_pk_fma_f32 v[8:9], v[32:33], v[10:11], v[8:9]
	s_waitcnt lgkmcnt(6)
	v_pk_fma_f32 v[10:11], v[68:69], v[140:141], v[12:13]
	v_pk_fma_f32 v[8:9], v[26:27], v[140:141], v[8:9]
	v_pk_fma_f32 v[10:11], v[66:67], v[142:143], v[10:11]
	v_pk_fma_f32 v[8:9], v[28:29], v[142:143], v[8:9]
	s_waitcnt lgkmcnt(5)
	v_pk_fma_f32 v[10:11], v[72:73], v[144:145], v[10:11]
	v_pk_fma_f32 v[8:9], v[22:23], v[144:145], v[8:9]
	v_pk_fma_f32 v[10:11], v[70:71], v[146:147], v[10:11]
	v_pk_fma_f32 v[8:9], v[24:25], v[146:147], v[8:9]
	s_waitcnt lgkmcnt(4)
	v_pk_fma_f32 v[10:11], v[50:51], v[148:149], v[10:11]
	v_pk_fma_f32 v[8:9], v[18:19], v[148:149], v[8:9]
	v_pk_fma_f32 v[10:11], v[52:53], v[150:151], v[10:11]
	v_pk_fma_f32 v[8:9], v[20:21], v[150:151], v[8:9]
	s_waitcnt lgkmcnt(3)
	v_pk_fma_f32 v[10:11], v[46:47], v[152:153], v[10:11]
	v_pk_fma_f32 v[8:9], v[14:15], v[152:153], v[8:9]
	v_pk_fma_f32 v[10:11], v[48:49], v[154:155], v[10:11]
	v_pk_fma_f32 v[8:9], v[16:17], v[154:155], v[8:9]
	s_waitcnt lgkmcnt(2)
	v_pk_fma_f32 v[10:11], v[42:43], v[156:157], v[10:11]
	v_pk_fma_f32 v[8:9], v[76:77], v[156:157], v[8:9]
	v_pk_fma_f32 v[10:11], v[44:45], v[158:159], v[10:11]
	v_pk_fma_f32 v[8:9], v[74:75], v[158:159], v[8:9]
	s_waitcnt lgkmcnt(1)
	v_pk_fma_f32 v[10:11], v[38:39], v[160:161], v[10:11]
	v_pk_fma_f32 v[8:9], v[80:81], v[160:161], v[8:9]
	v_pk_fma_f32 v[10:11], v[40:41], v[162:163], v[10:11]
	v_pk_fma_f32 v[8:9], v[78:79], v[162:163], v[8:9]
	s_waitcnt lgkmcnt(0)
	v_pk_fma_f32 v[10:11], v[34:35], v[164:165], v[10:11]
	v_pk_fma_f32 v[8:9], v[2:3], v[164:165], v[8:9]
	v_pk_fma_f32 v[10:11], v[36:37], v[166:167], v[10:11]
	v_pk_fma_f32 v[8:9], v[4:5], v[166:167], v[8:9]
	v_add_f32_e32 v198, v10, v11
	v_add_f32_e32 v7, v8, v9
	ds_read_b128 v[8:11], v97 offset:16384
	ds_read_b128 v[140:143], v97 offset:17408
	ds_read_b128 v[144:147], v97 offset:18432
	ds_read_b128 v[148:151], v97 offset:19456
	ds_read_b128 v[152:155], v97 offset:20480
	ds_read_b128 v[156:159], v97 offset:21504
	ds_read_b128 v[160:163], v97 offset:22528
	ds_read_b128 v[164:167], v97 offset:23552
	s_waitcnt lgkmcnt(7)
	v_pk_fma_f32 v[12:13], v[64:65], v[8:9], 0 op_sel_hi:[1,1,0]
	v_pk_fma_f32 v[8:9], v[30:31], v[8:9], 0 op_sel_hi:[1,1,0]
	v_pk_fma_f32 v[12:13], v[62:63], v[10:11], v[12:13]
	v_pk_fma_f32 v[8:9], v[32:33], v[10:11], v[8:9]
	s_waitcnt lgkmcnt(6)
	v_pk_fma_f32 v[10:11], v[68:69], v[140:141], v[12:13]
	v_pk_fma_f32 v[8:9], v[26:27], v[140:141], v[8:9]
	v_pk_fma_f32 v[10:11], v[66:67], v[142:143], v[10:11]
	v_pk_fma_f32 v[8:9], v[28:29], v[142:143], v[8:9]
	s_waitcnt lgkmcnt(5)
	v_pk_fma_f32 v[10:11], v[72:73], v[144:145], v[10:11]
	v_pk_fma_f32 v[8:9], v[22:23], v[144:145], v[8:9]
	v_pk_fma_f32 v[10:11], v[70:71], v[146:147], v[10:11]
	v_pk_fma_f32 v[8:9], v[24:25], v[146:147], v[8:9]
	s_waitcnt lgkmcnt(4)
	v_pk_fma_f32 v[10:11], v[50:51], v[148:149], v[10:11]
	v_pk_fma_f32 v[8:9], v[18:19], v[148:149], v[8:9]
	v_pk_fma_f32 v[10:11], v[52:53], v[150:151], v[10:11]
	v_pk_fma_f32 v[8:9], v[20:21], v[150:151], v[8:9]
	s_waitcnt lgkmcnt(3)
	v_pk_fma_f32 v[10:11], v[46:47], v[152:153], v[10:11]
	v_pk_fma_f32 v[8:9], v[14:15], v[152:153], v[8:9]
	v_pk_fma_f32 v[10:11], v[48:49], v[154:155], v[10:11]
	v_pk_fma_f32 v[8:9], v[16:17], v[154:155], v[8:9]
	s_waitcnt lgkmcnt(2)
	v_pk_fma_f32 v[10:11], v[42:43], v[156:157], v[10:11]
	v_pk_fma_f32 v[8:9], v[76:77], v[156:157], v[8:9]
	v_pk_fma_f32 v[10:11], v[44:45], v[158:159], v[10:11]
	v_pk_fma_f32 v[8:9], v[74:75], v[158:159], v[8:9]
	s_waitcnt lgkmcnt(1)
	v_pk_fma_f32 v[10:11], v[38:39], v[160:161], v[10:11]
	v_pk_fma_f32 v[8:9], v[80:81], v[160:161], v[8:9]
	v_pk_fma_f32 v[10:11], v[40:41], v[162:163], v[10:11]
	v_pk_fma_f32 v[8:9], v[78:79], v[162:163], v[8:9]
	s_waitcnt lgkmcnt(0)
	v_pk_fma_f32 v[10:11], v[34:35], v[164:165], v[10:11]
	v_pk_fma_f32 v[8:9], v[2:3], v[164:165], v[8:9]
	v_pk_fma_f32 v[10:11], v[36:37], v[166:167], v[10:11]
	v_pk_fma_f32 v[8:9], v[4:5], v[166:167], v[8:9]
	v_add_f32_e32 v199, v10, v11
	v_add_f32_e32 v8, v8, v9
	ds_read_b128 v[10:13], v97 offset:24576
	ds_read_b128 v[140:143], v97 offset:25600
	ds_read_b128 v[144:147], v97 offset:26624
	ds_read_b128 v[148:151], v97 offset:27648
	ds_read_b128 v[152:155], v97 offset:28672
	ds_read_b128 v[156:159], v97 offset:29696
	ds_read_b128 v[160:163], v97 offset:30720
	ds_read_b128 v[164:167], v97 offset:31744
	s_waitcnt lgkmcnt(7)
	v_pk_fma_f32 v[82:83], v[64:65], v[10:11], 0 op_sel_hi:[1,1,0]
	v_pk_fma_f32 v[10:11], v[30:31], v[10:11], 0 op_sel_hi:[1,1,0]
	v_pk_fma_f32 v[82:83], v[62:63], v[12:13], v[82:83]
	v_pk_fma_f32 v[10:11], v[32:33], v[12:13], v[10:11]
	s_waitcnt lgkmcnt(6)
	v_pk_fma_f32 v[12:13], v[68:69], v[140:141], v[82:83]
	v_pk_fma_f32 v[10:11], v[26:27], v[140:141], v[10:11]
	v_pk_fma_f32 v[12:13], v[66:67], v[142:143], v[12:13]
	v_pk_fma_f32 v[10:11], v[28:29], v[142:143], v[10:11]
	s_waitcnt lgkmcnt(5)
	v_pk_fma_f32 v[12:13], v[72:73], v[144:145], v[12:13]
	v_pk_fma_f32 v[10:11], v[22:23], v[144:145], v[10:11]
	v_pk_fma_f32 v[12:13], v[70:71], v[146:147], v[12:13]
	v_pk_fma_f32 v[10:11], v[24:25], v[146:147], v[10:11]
	s_waitcnt lgkmcnt(4)
	v_pk_fma_f32 v[12:13], v[50:51], v[148:149], v[12:13]
	v_pk_fma_f32 v[10:11], v[18:19], v[148:149], v[10:11]
	v_pk_fma_f32 v[12:13], v[52:53], v[150:151], v[12:13]
	v_pk_fma_f32 v[10:11], v[20:21], v[150:151], v[10:11]
	s_waitcnt lgkmcnt(3)
	v_pk_fma_f32 v[12:13], v[46:47], v[152:153], v[12:13]
	v_pk_fma_f32 v[10:11], v[14:15], v[152:153], v[10:11]
	v_pk_fma_f32 v[12:13], v[48:49], v[154:155], v[12:13]
	v_pk_fma_f32 v[10:11], v[16:17], v[154:155], v[10:11]
	s_waitcnt lgkmcnt(2)
	v_pk_fma_f32 v[12:13], v[42:43], v[156:157], v[12:13]
	v_pk_fma_f32 v[10:11], v[76:77], v[156:157], v[10:11]
	v_pk_fma_f32 v[12:13], v[44:45], v[158:159], v[12:13]
	v_pk_fma_f32 v[10:11], v[74:75], v[158:159], v[10:11]
	s_waitcnt lgkmcnt(1)
	v_pk_fma_f32 v[12:13], v[38:39], v[160:161], v[12:13]
	v_pk_fma_f32 v[10:11], v[80:81], v[160:161], v[10:11]
	v_pk_fma_f32 v[12:13], v[40:41], v[162:163], v[12:13]
	v_pk_fma_f32 v[10:11], v[78:79], v[162:163], v[10:11]
	s_waitcnt lgkmcnt(0)
	v_pk_fma_f32 v[12:13], v[34:35], v[164:165], v[12:13]
	v_pk_fma_f32 v[10:11], v[2:3], v[164:165], v[10:11]
	v_pk_fma_f32 v[12:13], v[36:37], v[166:167], v[12:13]
	v_pk_fma_f32 v[10:11], v[4:5], v[166:167], v[10:11]
	v_add_f32_e32 v200, v12, v13
	v_add_f32_e32 v9, v10, v11
	ds_read_b128 v[10:13], v97 offset:32768
	ds_read_b128 v[140:143], v97 offset:33792
	ds_read_b128 v[144:147], v97 offset:34816
	ds_read_b128 v[148:151], v97 offset:35840
	ds_read_b128 v[152:155], v97 offset:36864
	ds_read_b128 v[156:159], v97 offset:37888
	ds_read_b128 v[160:163], v97 offset:38912
	ds_read_b128 v[164:167], v97 offset:39936
	s_waitcnt lgkmcnt(7)
	v_pk_fma_f32 v[82:83], v[64:65], v[10:11], 0 op_sel_hi:[1,1,0]
	v_pk_fma_f32 v[10:11], v[30:31], v[10:11], 0 op_sel_hi:[1,1,0]
	v_pk_fma_f32 v[82:83], v[62:63], v[12:13], v[82:83]
	v_pk_fma_f32 v[10:11], v[32:33], v[12:13], v[10:11]
	s_waitcnt lgkmcnt(6)
	v_pk_fma_f32 v[12:13], v[68:69], v[140:141], v[82:83]
	v_pk_fma_f32 v[10:11], v[26:27], v[140:141], v[10:11]
	v_pk_fma_f32 v[12:13], v[66:67], v[142:143], v[12:13]
	v_pk_fma_f32 v[10:11], v[28:29], v[142:143], v[10:11]
	s_waitcnt lgkmcnt(5)
	v_pk_fma_f32 v[12:13], v[72:73], v[144:145], v[12:13]
	v_pk_fma_f32 v[10:11], v[22:23], v[144:145], v[10:11]
	v_pk_fma_f32 v[12:13], v[70:71], v[146:147], v[12:13]
	v_pk_fma_f32 v[10:11], v[24:25], v[146:147], v[10:11]
	s_waitcnt lgkmcnt(4)
	v_pk_fma_f32 v[12:13], v[50:51], v[148:149], v[12:13]
	v_pk_fma_f32 v[10:11], v[18:19], v[148:149], v[10:11]
	v_pk_fma_f32 v[12:13], v[52:53], v[150:151], v[12:13]
	v_pk_fma_f32 v[10:11], v[20:21], v[150:151], v[10:11]
	s_waitcnt lgkmcnt(3)
	v_pk_fma_f32 v[12:13], v[46:47], v[152:153], v[12:13]
	v_pk_fma_f32 v[10:11], v[14:15], v[152:153], v[10:11]
	v_pk_fma_f32 v[12:13], v[48:49], v[154:155], v[12:13]
	v_pk_fma_f32 v[10:11], v[16:17], v[154:155], v[10:11]
	s_waitcnt lgkmcnt(2)
	v_pk_fma_f32 v[12:13], v[42:43], v[156:157], v[12:13]
	v_pk_fma_f32 v[10:11], v[76:77], v[156:157], v[10:11]
	v_pk_fma_f32 v[12:13], v[44:45], v[158:159], v[12:13]
	v_pk_fma_f32 v[10:11], v[74:75], v[158:159], v[10:11]
	s_waitcnt lgkmcnt(1)
	v_pk_fma_f32 v[12:13], v[38:39], v[160:161], v[12:13]
	v_pk_fma_f32 v[10:11], v[80:81], v[160:161], v[10:11]
	v_pk_fma_f32 v[12:13], v[40:41], v[162:163], v[12:13]
	v_pk_fma_f32 v[10:11], v[78:79], v[162:163], v[10:11]
	s_waitcnt lgkmcnt(0)
	v_pk_fma_f32 v[12:13], v[34:35], v[164:165], v[12:13]
	v_pk_fma_f32 v[10:11], v[2:3], v[164:165], v[10:11]
	v_pk_fma_f32 v[12:13], v[36:37], v[166:167], v[12:13]
	v_pk_fma_f32 v[10:11], v[4:5], v[166:167], v[10:11]
	v_add_f32_e32 v201, v12, v13
	v_add_f32_e32 v10, v10, v11
	ds_read_b128 v[140:143], v97 offset:40960
	ds_read_b128 v[144:147], v97 offset:41984
	ds_read_b128 v[148:151], v97 offset:43008
	ds_read_b128 v[152:155], v97 offset:44032
	ds_read_b128 v[156:159], v97 offset:45056
	ds_read_b128 v[160:163], v97 offset:46080
	ds_read_b128 v[164:167], v97 offset:47104
	ds_read_b128 v[168:171], v97 offset:48128
	s_waitcnt lgkmcnt(7)
	v_pk_fma_f32 v[12:13], v[64:65], v[140:141], 0 op_sel_hi:[1,1,0]
	v_pk_fma_f32 v[82:83], v[30:31], v[140:141], 0 op_sel_hi:[1,1,0]
	v_pk_fma_f32 v[12:13], v[62:63], v[142:143], v[12:13]
	v_pk_fma_f32 v[82:83], v[32:33], v[142:143], v[82:83]
	s_waitcnt lgkmcnt(6)
	v_pk_fma_f32 v[12:13], v[68:69], v[144:145], v[12:13]
	v_pk_fma_f32 v[82:83], v[26:27], v[144:145], v[82:83]
	v_pk_fma_f32 v[12:13], v[66:67], v[146:147], v[12:13]
	v_pk_fma_f32 v[82:83], v[28:29], v[146:147], v[82:83]
	s_waitcnt lgkmcnt(5)
	v_pk_fma_f32 v[12:13], v[72:73], v[148:149], v[12:13]
	v_pk_fma_f32 v[82:83], v[22:23], v[148:149], v[82:83]
	v_pk_fma_f32 v[12:13], v[70:71], v[150:151], v[12:13]
	v_pk_fma_f32 v[82:83], v[24:25], v[150:151], v[82:83]
	s_waitcnt lgkmcnt(4)
	v_pk_fma_f32 v[12:13], v[50:51], v[152:153], v[12:13]
	v_pk_fma_f32 v[82:83], v[18:19], v[152:153], v[82:83]
	v_pk_fma_f32 v[12:13], v[52:53], v[154:155], v[12:13]
	v_pk_fma_f32 v[82:83], v[20:21], v[154:155], v[82:83]
	s_waitcnt lgkmcnt(3)
	v_pk_fma_f32 v[12:13], v[46:47], v[156:157], v[12:13]
	v_pk_fma_f32 v[82:83], v[14:15], v[156:157], v[82:83]
	v_pk_fma_f32 v[12:13], v[48:49], v[158:159], v[12:13]
	v_pk_fma_f32 v[82:83], v[16:17], v[158:159], v[82:83]
	s_waitcnt lgkmcnt(2)
	v_pk_fma_f32 v[12:13], v[42:43], v[160:161], v[12:13]
	v_pk_fma_f32 v[82:83], v[76:77], v[160:161], v[82:83]
	v_pk_fma_f32 v[12:13], v[44:45], v[162:163], v[12:13]
	v_pk_fma_f32 v[82:83], v[74:75], v[162:163], v[82:83]
	s_waitcnt lgkmcnt(1)
	v_pk_fma_f32 v[12:13], v[38:39], v[164:165], v[12:13]
	v_pk_fma_f32 v[82:83], v[80:81], v[164:165], v[82:83]
	v_pk_fma_f32 v[12:13], v[40:41], v[166:167], v[12:13]
	v_pk_fma_f32 v[82:83], v[78:79], v[166:167], v[82:83]
	s_waitcnt lgkmcnt(0)
	v_pk_fma_f32 v[12:13], v[34:35], v[168:169], v[12:13]
	v_pk_fma_f32 v[82:83], v[2:3], v[168:169], v[82:83]
	v_pk_fma_f32 v[12:13], v[36:37], v[170:171], v[12:13]
	v_pk_fma_f32 v[82:83], v[4:5], v[170:171], v[82:83]
	v_add_f32_e32 v202, v12, v13
	v_add_f32_e32 v11, v82, v83
	ds_read_b128 v[140:143], v97 offset:49152
	ds_read_b128 v[144:147], v97 offset:50176
	ds_read_b128 v[148:151], v97 offset:51200
	ds_read_b128 v[152:155], v97 offset:52224
	ds_read_b128 v[156:159], v97 offset:53248
	ds_read_b128 v[160:163], v97 offset:54272
	ds_read_b128 v[164:167], v97 offset:55296
	ds_read_b128 v[168:171], v97 offset:56320
	s_waitcnt lgkmcnt(7)
	v_pk_fma_f32 v[12:13], v[64:65], v[140:141], 0 op_sel_hi:[1,1,0]
	v_pk_fma_f32 v[82:83], v[30:31], v[140:141], 0 op_sel_hi:[1,1,0]
	v_pk_fma_f32 v[12:13], v[62:63], v[142:143], v[12:13]
	v_pk_fma_f32 v[82:83], v[32:33], v[142:143], v[82:83]
	s_waitcnt lgkmcnt(6)
	v_pk_fma_f32 v[12:13], v[68:69], v[144:145], v[12:13]
	v_pk_fma_f32 v[82:83], v[26:27], v[144:145], v[82:83]
	v_pk_fma_f32 v[12:13], v[66:67], v[146:147], v[12:13]
	v_pk_fma_f32 v[82:83], v[28:29], v[146:147], v[82:83]
	s_waitcnt lgkmcnt(5)
	v_pk_fma_f32 v[12:13], v[72:73], v[148:149], v[12:13]
	v_pk_fma_f32 v[82:83], v[22:23], v[148:149], v[82:83]
	v_pk_fma_f32 v[12:13], v[70:71], v[150:151], v[12:13]
	v_pk_fma_f32 v[82:83], v[24:25], v[150:151], v[82:83]
	s_waitcnt lgkmcnt(4)
	v_pk_fma_f32 v[12:13], v[50:51], v[152:153], v[12:13]
	v_pk_fma_f32 v[82:83], v[18:19], v[152:153], v[82:83]
	v_pk_fma_f32 v[12:13], v[52:53], v[154:155], v[12:13]
	v_pk_fma_f32 v[82:83], v[20:21], v[154:155], v[82:83]
	s_waitcnt lgkmcnt(3)
	v_pk_fma_f32 v[12:13], v[46:47], v[156:157], v[12:13]
	v_pk_fma_f32 v[82:83], v[14:15], v[156:157], v[82:83]
	v_pk_fma_f32 v[12:13], v[48:49], v[158:159], v[12:13]
	v_pk_fma_f32 v[82:83], v[16:17], v[158:159], v[82:83]
	s_waitcnt lgkmcnt(2)
	v_pk_fma_f32 v[12:13], v[42:43], v[160:161], v[12:13]
	v_pk_fma_f32 v[82:83], v[76:77], v[160:161], v[82:83]
	v_pk_fma_f32 v[12:13], v[44:45], v[162:163], v[12:13]
	v_pk_fma_f32 v[82:83], v[74:75], v[162:163], v[82:83]
	s_waitcnt lgkmcnt(1)
	v_pk_fma_f32 v[12:13], v[38:39], v[164:165], v[12:13]
	v_pk_fma_f32 v[82:83], v[80:81], v[164:165], v[82:83]
	v_pk_fma_f32 v[12:13], v[40:41], v[166:167], v[12:13]
	v_pk_fma_f32 v[82:83], v[78:79], v[166:167], v[82:83]
	s_waitcnt lgkmcnt(0)
	v_pk_fma_f32 v[12:13], v[34:35], v[168:169], v[12:13]
	v_pk_fma_f32 v[82:83], v[2:3], v[168:169], v[82:83]
	v_pk_fma_f32 v[12:13], v[36:37], v[170:171], v[12:13]
	v_pk_fma_f32 v[82:83], v[4:5], v[170:171], v[82:83]
	v_add_f32_e32 v203, v12, v13
	v_add_f32_e32 v12, v82, v83
	ds_read_b128 v[140:143], v97 offset:57344
	ds_read_b128 v[144:147], v97 offset:58368
	ds_read_b128 v[148:151], v97 offset:59392
	ds_read_b128 v[152:155], v97 offset:60416
	ds_read_b128 v[156:159], v97 offset:61440
	ds_read_b128 v[160:163], v97 offset:62464
	ds_read_b128 v[164:167], v97 offset:63488
	ds_read_b128 v[168:171], v97 offset:64512
	s_waitcnt lgkmcnt(7)
	v_pk_fma_f32 v[82:83], v[64:65], v[140:141], 0 op_sel_hi:[1,1,0]
	v_pk_fma_f32 v[140:141], v[30:31], v[140:141], 0 op_sel_hi:[1,1,0]
	v_pk_fma_f32 v[82:83], v[62:63], v[142:143], v[82:83]
	v_pk_fma_f32 v[140:141], v[32:33], v[142:143], v[140:141]
	s_waitcnt lgkmcnt(6)
	v_pk_fma_f32 v[82:83], v[68:69], v[144:145], v[82:83]
	v_pk_fma_f32 v[140:141], v[26:27], v[144:145], v[140:141]
	v_pk_fma_f32 v[82:83], v[66:67], v[146:147], v[82:83]
	v_pk_fma_f32 v[140:141], v[28:29], v[146:147], v[140:141]
	s_waitcnt lgkmcnt(5)
	v_pk_fma_f32 v[82:83], v[72:73], v[148:149], v[82:83]
	v_pk_fma_f32 v[140:141], v[22:23], v[148:149], v[140:141]
	v_pk_fma_f32 v[82:83], v[70:71], v[150:151], v[82:83]
	v_pk_fma_f32 v[140:141], v[24:25], v[150:151], v[140:141]
	s_waitcnt lgkmcnt(4)
	v_pk_fma_f32 v[82:83], v[50:51], v[152:153], v[82:83]
	v_pk_fma_f32 v[140:141], v[18:19], v[152:153], v[140:141]
	v_pk_fma_f32 v[82:83], v[52:53], v[154:155], v[82:83]
	v_pk_fma_f32 v[140:141], v[20:21], v[154:155], v[140:141]
	s_waitcnt lgkmcnt(3)
	v_pk_fma_f32 v[82:83], v[46:47], v[156:157], v[82:83]
	v_pk_fma_f32 v[140:141], v[14:15], v[156:157], v[140:141]
	v_pk_fma_f32 v[82:83], v[48:49], v[158:159], v[82:83]
	v_pk_fma_f32 v[140:141], v[16:17], v[158:159], v[140:141]
	s_waitcnt lgkmcnt(2)
	v_pk_fma_f32 v[82:83], v[42:43], v[160:161], v[82:83]
	v_pk_fma_f32 v[140:141], v[76:77], v[160:161], v[140:141]
	v_pk_fma_f32 v[82:83], v[44:45], v[162:163], v[82:83]
	v_pk_fma_f32 v[140:141], v[74:75], v[162:163], v[140:141]
	s_waitcnt lgkmcnt(1)
	v_pk_fma_f32 v[82:83], v[38:39], v[164:165], v[82:83]
	v_pk_fma_f32 v[140:141], v[80:81], v[164:165], v[140:141]
	v_pk_fma_f32 v[82:83], v[40:41], v[166:167], v[82:83]
	v_pk_fma_f32 v[140:141], v[78:79], v[166:167], v[140:141]
	s_waitcnt lgkmcnt(0)
	v_pk_fma_f32 v[82:83], v[34:35], v[168:169], v[82:83]
	v_pk_fma_f32 v[140:141], v[2:3], v[168:169], v[140:141]
	v_pk_fma_f32 v[82:83], v[36:37], v[170:171], v[82:83]
	v_pk_fma_f32 v[140:141], v[4:5], v[170:171], v[140:141]
	v_add_f32_e32 v204, v82, v83
	v_add_f32_e32 v13, v140, v141
	v_add_u32_e32 v173, 0x10000, v97
	v_add_u32_e32 v174, 0x10400, v97
	v_add_u32_e32 v175, 0x10800, v97
	v_add_u32_e32 v176, 0x10c00, v97
	v_add_u32_e32 v177, 0x11000, v97
	v_add_u32_e32 v178, 0x11400, v97
	v_add_u32_e32 v179, 0x11800, v97
	v_add_u32_e32 v180, 0x11c00, v97
	ds_read_b128 v[140:143], v173
	ds_read_b128 v[144:147], v174
	ds_read_b128 v[148:151], v175
	ds_read_b128 v[152:155], v176
	ds_read_b128 v[156:159], v177
	ds_read_b128 v[160:163], v178
	ds_read_b128 v[164:167], v179
	ds_read_b128 v[168:171], v180
	s_waitcnt lgkmcnt(7)
	v_pk_fma_f32 v[82:83], v[64:65], v[140:141], 0 op_sel_hi:[1,1,0]
	v_pk_fma_f32 v[140:141], v[30:31], v[140:141], 0 op_sel_hi:[1,1,0]
	v_pk_fma_f32 v[82:83], v[62:63], v[142:143], v[82:83]
	v_pk_fma_f32 v[140:141], v[32:33], v[142:143], v[140:141]
	s_waitcnt lgkmcnt(6)
	v_pk_fma_f32 v[82:83], v[68:69], v[144:145], v[82:83]
	v_pk_fma_f32 v[140:141], v[26:27], v[144:145], v[140:141]
	v_pk_fma_f32 v[82:83], v[66:67], v[146:147], v[82:83]
	v_pk_fma_f32 v[140:141], v[28:29], v[146:147], v[140:141]
	s_waitcnt lgkmcnt(5)
	v_pk_fma_f32 v[82:83], v[72:73], v[148:149], v[82:83]
	v_pk_fma_f32 v[140:141], v[22:23], v[148:149], v[140:141]
	v_pk_fma_f32 v[82:83], v[70:71], v[150:151], v[82:83]
	v_pk_fma_f32 v[140:141], v[24:25], v[150:151], v[140:141]
	s_waitcnt lgkmcnt(4)
	v_pk_fma_f32 v[82:83], v[50:51], v[152:153], v[82:83]
	v_pk_fma_f32 v[140:141], v[18:19], v[152:153], v[140:141]
	v_pk_fma_f32 v[82:83], v[52:53], v[154:155], v[82:83]
	v_pk_fma_f32 v[140:141], v[20:21], v[154:155], v[140:141]
	s_waitcnt lgkmcnt(3)
	v_pk_fma_f32 v[82:83], v[46:47], v[156:157], v[82:83]
	v_pk_fma_f32 v[140:141], v[14:15], v[156:157], v[140:141]
	v_pk_fma_f32 v[82:83], v[48:49], v[158:159], v[82:83]
	v_pk_fma_f32 v[140:141], v[16:17], v[158:159], v[140:141]
	s_waitcnt lgkmcnt(2)
	v_pk_fma_f32 v[82:83], v[42:43], v[160:161], v[82:83]
	v_pk_fma_f32 v[140:141], v[76:77], v[160:161], v[140:141]
	v_pk_fma_f32 v[82:83], v[44:45], v[162:163], v[82:83]
	v_pk_fma_f32 v[140:141], v[74:75], v[162:163], v[140:141]
	s_waitcnt lgkmcnt(1)
	v_pk_fma_f32 v[82:83], v[38:39], v[164:165], v[82:83]
	v_pk_fma_f32 v[140:141], v[80:81], v[164:165], v[140:141]
	v_pk_fma_f32 v[82:83], v[40:41], v[166:167], v[82:83]
	v_pk_fma_f32 v[140:141], v[78:79], v[166:167], v[140:141]
	s_waitcnt lgkmcnt(0)
	v_pk_fma_f32 v[82:83], v[34:35], v[168:169], v[82:83]
	v_pk_fma_f32 v[140:141], v[2:3], v[168:169], v[140:141]
	v_pk_fma_f32 v[82:83], v[36:37], v[170:171], v[82:83]
	v_pk_fma_f32 v[140:141], v[4:5], v[170:171], v[140:141]
	v_add_f32_e32 v83, v82, v83
	v_add_f32_e32 v82, v140, v141
	v_add_u32_e32 v181, 0x12000, v97
	v_and_b32_e32 v172, 32, v60
	v_add_u32_e32 v182, 0x12400, v97
	v_add_u32_e32 v183, 0x12800, v97
	v_add_u32_e32 v184, 0x12c00, v97
	v_add_u32_e32 v185, 0x13000, v97
	v_add_u32_e32 v186, 0x13400, v97
	v_add_u32_e32 v187, 0x13800, v97
	v_add_u32_e32 v188, 0x13c00, v97
	ds_read_b128 v[140:143], v181
	ds_read_b128 v[144:147], v182
	ds_read_b128 v[148:151], v183
	ds_read_b128 v[152:155], v184
	ds_read_b128 v[156:159], v185
	ds_read_b128 v[160:163], v186
	ds_read_b128 v[164:167], v187
	ds_read_b128 v[168:171], v188
	v_cndmask_b32_e32 v96, v55, v89, vcc
	v_cmp_eq_u32_e32 vcc, 0, v172
	s_waitcnt lgkmcnt(7)
	v_pk_fma_f32 v[172:173], v[64:65], v[140:141], 0 op_sel_hi:[1,1,0]
	v_pk_fma_f32 v[140:141], v[30:31], v[140:141], 0 op_sel_hi:[1,1,0]
	v_pk_fma_f32 v[172:173], v[62:63], v[142:143], v[172:173]
	v_pk_fma_f32 v[140:141], v[32:33], v[142:143], v[140:141]
	s_waitcnt lgkmcnt(6)
	v_pk_fma_f32 v[142:143], v[68:69], v[144:145], v[172:173]
	v_pk_fma_f32 v[140:141], v[26:27], v[144:145], v[140:141]
	v_pk_fma_f32 v[142:143], v[66:67], v[146:147], v[142:143]
	v_pk_fma_f32 v[140:141], v[28:29], v[146:147], v[140:141]
	s_waitcnt lgkmcnt(5)
	v_pk_fma_f32 v[142:143], v[72:73], v[148:149], v[142:143]
	v_pk_fma_f32 v[140:141], v[22:23], v[148:149], v[140:141]
	v_pk_fma_f32 v[142:143], v[70:71], v[150:151], v[142:143]
	v_pk_fma_f32 v[140:141], v[24:25], v[150:151], v[140:141]
	s_waitcnt lgkmcnt(4)
	v_pk_fma_f32 v[142:143], v[50:51], v[152:153], v[142:143]
	v_pk_fma_f32 v[140:141], v[18:19], v[152:153], v[140:141]
	v_pk_fma_f32 v[142:143], v[52:53], v[154:155], v[142:143]
	v_pk_fma_f32 v[140:141], v[20:21], v[154:155], v[140:141]
	s_waitcnt lgkmcnt(3)
	v_pk_fma_f32 v[142:143], v[46:47], v[156:157], v[142:143]
	v_pk_fma_f32 v[140:141], v[14:15], v[156:157], v[140:141]
	v_pk_fma_f32 v[142:143], v[48:49], v[158:159], v[142:143]
	v_pk_fma_f32 v[140:141], v[16:17], v[158:159], v[140:141]
	v_add_u32_e32 v189, 0x14000, v97
	v_add_u32_e32 v190, 0x14400, v97
	v_add_u32_e32 v191, 0x14800, v97
	v_add_u32_e32 v192, 0x14c00, v97
	v_add_u32_e32 v193, 0x15000, v97
	v_add_u32_e32 v194, 0x15400, v97
	v_add_u32_e32 v195, 0x15800, v97
	v_add_u32_e32 v196, 0x15c00, v97
	v_add_u32_e32 v98, 0x16000, v97
	v_add_u32_e32 v133, 0x16400, v97
	v_add_u32_e32 v134, 0x16800, v97
	v_add_u32_e32 v135, 0x16c00, v97
	v_add_u32_e32 v136, 0x17000, v97
	v_add_u32_e32 v137, 0x17400, v97
	v_add_u32_e32 v138, 0x17800, v97
	v_add_u32_e32 v139, 0x17c00, v97
	v_add_u32_e32 v99, 0x18000, v97
	v_add_u32_e32 v126, 0x18400, v97
	v_add_u32_e32 v127, 0x18800, v97
	v_add_u32_e32 v128, 0x18c00, v97
	v_add_u32_e32 v129, 0x19000, v97
	v_add_u32_e32 v130, 0x19400, v97
	v_add_u32_e32 v131, 0x19800, v97
	v_add_u32_e32 v132, 0x19c00, v97
	v_add_u32_e32 v118, 0x1a000, v97
	v_add_u32_e32 v119, 0x1a400, v97
	v_add_u32_e32 v120, 0x1a800, v97
	v_add_u32_e32 v121, 0x1ac00, v97
	v_add_u32_e32 v122, 0x1b000, v97
	v_add_u32_e32 v123, 0x1b400, v97
	v_add_u32_e32 v124, 0x1b800, v97
	v_add_u32_e32 v125, 0x1bc00, v97
	v_add_u32_e32 v101, 0x1c000, v97
	v_add_u32_e32 v111, 0x1c400, v97
	v_add_u32_e32 v112, 0x1c800, v97
	v_add_u32_e32 v113, 0x1cc00, v97
	v_add_u32_e32 v114, 0x1d000, v97
	v_add_u32_e32 v115, 0x1d400, v97
	v_add_u32_e32 v116, 0x1d800, v97
	v_add_u32_e32 v117, 0x1dc00, v97
	v_add_u32_e32 v103, 0x1e000, v97
	v_add_u32_e32 v104, 0x1e400, v97
	v_add_u32_e32 v105, 0x1e800, v97
	v_add_u32_e32 v106, 0x1ec00, v97
	v_add_u32_e32 v107, 0x1f000, v97
	v_add_u32_e32 v108, 0x1f400, v97
	v_add_u32_e32 v109, 0x1f800, v97
	v_add_u32_e32 v110, 0x1fc00, v97
	v_cndmask_b32_e32 v97, v83, v197, vcc
	v_cndmask_b32_e32 v83, v197, v83, vcc
	s_waitcnt lgkmcnt(2)
	v_pk_fma_f32 v[142:143], v[42:43], v[160:161], v[142:143]
	v_pk_fma_f32 v[140:141], v[76:77], v[160:161], v[140:141]
	ds_bpermute_b32 v83, v95, v83
	v_pk_fma_f32 v[142:143], v[44:45], v[162:163], v[142:143]
	v_pk_fma_f32 v[140:141], v[74:75], v[162:163], v[140:141]
	s_waitcnt lgkmcnt(2)
	v_pk_fma_f32 v[142:143], v[38:39], v[164:165], v[142:143]
	v_pk_fma_f32 v[140:141], v[80:81], v[164:165], v[140:141]
	v_pk_fma_f32 v[142:143], v[40:41], v[166:167], v[142:143]
	v_pk_fma_f32 v[140:141], v[78:79], v[166:167], v[140:141]
	s_waitcnt lgkmcnt(1)
	v_pk_fma_f32 v[142:143], v[34:35], v[168:169], v[142:143]
	v_pk_fma_f32 v[140:141], v[2:3], v[168:169], v[140:141]
	v_pk_fma_f32 v[142:143], v[36:37], v[170:171], v[142:143]
	v_pk_fma_f32 v[140:141], v[4:5], v[170:171], v[140:141]
	s_waitcnt lgkmcnt(0)
	v_add_f32_e32 v174, v97, v83
	v_add_f32_e32 v97, v142, v143
	v_add_f32_e32 v83, v140, v141
	ds_read_b128 v[140:143], v189
	ds_read_b128 v[144:147], v190
	ds_read_b128 v[148:151], v191
	ds_read_b128 v[152:155], v192
	ds_read_b128 v[156:159], v193
	ds_read_b128 v[160:163], v194
	ds_read_b128 v[164:167], v195
	ds_read_b128 v[168:171], v196
	s_waitcnt lgkmcnt(7)
	v_pk_fma_f32 v[172:173], v[64:65], v[140:141], 0 op_sel_hi:[1,1,0]
	v_pk_fma_f32 v[140:141], v[30:31], v[140:141], 0 op_sel_hi:[1,1,0]
	v_pk_fma_f32 v[172:173], v[62:63], v[142:143], v[172:173]
	v_pk_fma_f32 v[140:141], v[32:33], v[142:143], v[140:141]
	s_waitcnt lgkmcnt(6)
	v_pk_fma_f32 v[142:143], v[68:69], v[144:145], v[172:173]
	v_pk_fma_f32 v[140:141], v[26:27], v[144:145], v[140:141]
	v_pk_fma_f32 v[142:143], v[66:67], v[146:147], v[142:143]
	v_pk_fma_f32 v[140:141], v[28:29], v[146:147], v[140:141]
	s_waitcnt lgkmcnt(5)
	v_pk_fma_f32 v[142:143], v[72:73], v[148:149], v[142:143]
	v_pk_fma_f32 v[140:141], v[22:23], v[148:149], v[140:141]
	v_pk_fma_f32 v[142:143], v[70:71], v[150:151], v[142:143]
	v_pk_fma_f32 v[140:141], v[24:25], v[150:151], v[140:141]
	s_waitcnt lgkmcnt(4)
	v_pk_fma_f32 v[142:143], v[50:51], v[152:153], v[142:143]
	v_pk_fma_f32 v[140:141], v[18:19], v[152:153], v[140:141]
	v_pk_fma_f32 v[142:143], v[52:53], v[154:155], v[142:143]
	v_pk_fma_f32 v[140:141], v[20:21], v[154:155], v[140:141]
	s_waitcnt lgkmcnt(3)
	v_pk_fma_f32 v[142:143], v[46:47], v[156:157], v[142:143]
	v_pk_fma_f32 v[140:141], v[14:15], v[156:157], v[140:141]
	v_pk_fma_f32 v[142:143], v[48:49], v[158:159], v[142:143]
	v_pk_fma_f32 v[140:141], v[16:17], v[158:159], v[140:141]
	v_cndmask_b32_e32 v175, v97, v198, vcc
	v_cndmask_b32_e32 v97, v198, v97, vcc
	s_waitcnt lgkmcnt(2)
	v_pk_fma_f32 v[142:143], v[42:43], v[160:161], v[142:143]
	v_pk_fma_f32 v[140:141], v[76:77], v[160:161], v[140:141]
	ds_bpermute_b32 v97, v95, v97
	v_pk_fma_f32 v[142:143], v[44:45], v[162:163], v[142:143]
	v_pk_fma_f32 v[140:141], v[74:75], v[162:163], v[140:141]
	s_waitcnt lgkmcnt(2)
	v_pk_fma_f32 v[142:143], v[38:39], v[164:165], v[142:143]
	v_pk_fma_f32 v[140:141], v[80:81], v[164:165], v[140:141]
	v_pk_fma_f32 v[142:143], v[40:41], v[166:167], v[142:143]
	v_pk_fma_f32 v[140:141], v[78:79], v[166:167], v[140:141]
	s_waitcnt lgkmcnt(1)
	v_pk_fma_f32 v[142:143], v[34:35], v[168:169], v[142:143]
	v_pk_fma_f32 v[140:141], v[2:3], v[168:169], v[140:141]
	v_pk_fma_f32 v[142:143], v[36:37], v[170:171], v[142:143]
	v_pk_fma_f32 v[140:141], v[4:5], v[170:171], v[140:141]
	s_waitcnt lgkmcnt(0)
	v_add_f32_e32 v172, v175, v97
	v_add_f32_e32 v168, v142, v143
	v_add_f32_e32 v97, v140, v141
	ds_read_b128 v[140:143], v98
	ds_read_b128 v[144:147], v133
	ds_read_b128 v[148:151], v134
	ds_read_b128 v[152:155], v135
	ds_read_b128 v[156:159], v136
	ds_read_b128 v[134:137], v137
	ds_read_b128 v[160:163], v138
	ds_read_b128 v[164:167], v139
	s_waitcnt lgkmcnt(7)
	v_pk_fma_f32 v[138:139], v[64:65], v[140:141], 0 op_sel_hi:[1,1,0]
	v_pk_fma_f32 v[140:141], v[30:31], v[140:141], 0 op_sel_hi:[1,1,0]
	v_pk_fma_f32 v[138:139], v[62:63], v[142:143], v[138:139]
	v_pk_fma_f32 v[140:141], v[32:33], v[142:143], v[140:141]
	s_waitcnt lgkmcnt(6)
	v_pk_fma_f32 v[138:139], v[68:69], v[144:145], v[138:139]
	v_pk_fma_f32 v[140:141], v[26:27], v[144:145], v[140:141]
	v_pk_fma_f32 v[138:139], v[66:67], v[146:147], v[138:139]
	v_pk_fma_f32 v[140:141], v[28:29], v[146:147], v[140:141]
	s_waitcnt lgkmcnt(5)
	v_pk_fma_f32 v[138:139], v[72:73], v[148:149], v[138:139]
	v_pk_fma_f32 v[140:141], v[22:23], v[148:149], v[140:141]
	v_pk_fma_f32 v[138:139], v[70:71], v[150:151], v[138:139]
	v_pk_fma_f32 v[140:141], v[24:25], v[150:151], v[140:141]
	s_waitcnt lgkmcnt(4)
	v_pk_fma_f32 v[138:139], v[50:51], v[152:153], v[138:139]
	v_pk_fma_f32 v[140:141], v[18:19], v[152:153], v[140:141]
	v_pk_fma_f32 v[138:139], v[52:53], v[154:155], v[138:139]
	v_pk_fma_f32 v[140:141], v[20:21], v[154:155], v[140:141]
	s_waitcnt lgkmcnt(3)
	v_pk_fma_f32 v[138:139], v[46:47], v[156:157], v[138:139]
	v_pk_fma_f32 v[140:141], v[14:15], v[156:157], v[140:141]
	v_pk_fma_f32 v[138:139], v[48:49], v[158:159], v[138:139]
	v_pk_fma_f32 v[140:141], v[16:17], v[158:159], v[140:141]
	v_cndmask_b32_e32 v133, v199, v168, vcc
	s_waitcnt lgkmcnt(2)
	v_pk_fma_f32 v[138:139], v[42:43], v[134:135], v[138:139]
	v_pk_fma_f32 v[134:135], v[76:77], v[134:135], v[140:141]
	ds_bpermute_b32 v133, v95, v133
	v_pk_fma_f32 v[138:139], v[44:45], v[136:137], v[138:139]
	v_pk_fma_f32 v[134:135], v[74:75], v[136:137], v[134:135]
	s_waitcnt lgkmcnt(2)
	v_pk_fma_f32 v[136:137], v[38:39], v[160:161], v[138:139]
	v_pk_fma_f32 v[134:135], v[80:81], v[160:161], v[134:135]
	v_pk_fma_f32 v[136:137], v[40:41], v[162:163], v[136:137]
	v_pk_fma_f32 v[134:135], v[78:79], v[162:163], v[134:135]
	s_waitcnt lgkmcnt(1)
	v_pk_fma_f32 v[136:137], v[34:35], v[164:165], v[136:137]
	v_pk_fma_f32 v[134:135], v[2:3], v[164:165], v[134:135]
	v_cndmask_b32_e32 v98, v168, v199, vcc
	v_pk_fma_f32 v[136:137], v[36:37], v[166:167], v[136:137]
	v_pk_fma_f32 v[134:135], v[4:5], v[166:167], v[134:135]
	s_waitcnt lgkmcnt(0)
	v_add_f32_e32 v168, v98, v133
	v_add_f32_e32 v158, v136, v137
	v_add_f32_e32 v98, v134, v135
	ds_read_b128 v[134:137], v99
	ds_read_b128 v[138:141], v126
	ds_read_b128 v[142:145], v127
	ds_read_b128 v[146:149], v128
	ds_read_b128 v[126:129], v129
	ds_read_b128 v[150:153], v130
	ds_read_b128 v[154:157], v131
	ds_read_b128 v[130:133], v132
	v_cndmask_b32_e32 v99, v158, v200, vcc
	v_cndmask_b32_e32 v158, v200, v158, vcc
	ds_bpermute_b32 v160, v95, v158
	s_waitcnt lgkmcnt(8)
	v_pk_fma_f32 v[158:159], v[64:65], v[134:135], 0 op_sel_hi:[1,1,0]
	v_pk_fma_f32 v[134:135], v[30:31], v[134:135], 0 op_sel_hi:[1,1,0]
	v_pk_fma_f32 v[158:159], v[62:63], v[136:137], v[158:159]
	v_pk_fma_f32 v[134:135], v[32:33], v[136:137], v[134:135]
	s_waitcnt lgkmcnt(7)
	v_pk_fma_f32 v[136:137], v[68:69], v[138:139], v[158:159]
	v_pk_fma_f32 v[134:135], v[26:27], v[138:139], v[134:135]
	v_pk_fma_f32 v[136:137], v[66:67], v[140:141], v[136:137]
	v_pk_fma_f32 v[134:135], v[28:29], v[140:141], v[134:135]
	s_waitcnt lgkmcnt(6)
	v_pk_fma_f32 v[136:137], v[72:73], v[142:143], v[136:137]
	v_pk_fma_f32 v[134:135], v[22:23], v[142:143], v[134:135]
	v_pk_fma_f32 v[136:137], v[70:71], v[144:145], v[136:137]
	v_pk_fma_f32 v[134:135], v[24:25], v[144:145], v[134:135]
	s_waitcnt lgkmcnt(5)
	v_pk_fma_f32 v[136:137], v[50:51], v[146:147], v[136:137]
	v_pk_fma_f32 v[134:135], v[18:19], v[146:147], v[134:135]
	v_pk_fma_f32 v[136:137], v[52:53], v[148:149], v[136:137]
	v_pk_fma_f32 v[134:135], v[20:21], v[148:149], v[134:135]
	s_waitcnt lgkmcnt(4)
	v_pk_fma_f32 v[136:137], v[46:47], v[126:127], v[136:137]
	v_pk_fma_f32 v[126:127], v[14:15], v[126:127], v[134:135]
	v_pk_fma_f32 v[134:135], v[48:49], v[128:129], v[136:137]
	v_pk_fma_f32 v[126:127], v[16:17], v[128:129], v[126:127]
	s_waitcnt lgkmcnt(3)
	v_pk_fma_f32 v[128:129], v[42:43], v[150:151], v[134:135]
	v_pk_fma_f32 v[126:127], v[76:77], v[150:151], v[126:127]
	v_pk_fma_f32 v[128:129], v[44:45], v[152:153], v[128:129]
	v_pk_fma_f32 v[126:127], v[74:75], v[152:153], v[126:127]
	s_waitcnt lgkmcnt(2)
	v_pk_fma_f32 v[128:129], v[38:39], v[154:155], v[128:129]
	v_pk_fma_f32 v[126:127], v[80:81], v[154:155], v[126:127]
	v_pk_fma_f32 v[128:129], v[40:41], v[156:157], v[128:129]
	v_pk_fma_f32 v[126:127], v[78:79], v[156:157], v[126:127]
	s_waitcnt lgkmcnt(1)
	v_pk_fma_f32 v[128:129], v[34:35], v[130:131], v[128:129]
	v_pk_fma_f32 v[126:127], v[2:3], v[130:131], v[126:127]
	v_pk_fma_f32 v[128:129], v[36:37], v[132:133], v[128:129]
	v_pk_fma_f32 v[126:127], v[4:5], v[132:133], v[126:127]
	s_waitcnt lgkmcnt(0)
	v_add_f32_e32 v158, v99, v160
	v_add_f32_e32 v150, v128, v129
	v_add_f32_e32 v99, v126, v127
	ds_read_b128 v[126:129], v118
	ds_read_b128 v[130:133], v119
	ds_read_b128 v[134:137], v120
	ds_read_b128 v[118:121], v121
	ds_read_b128 v[138:141], v122
	ds_read_b128 v[142:145], v123
	ds_read_b128 v[146:149], v124
	ds_read_b128 v[122:125], v125
	v_cndmask_b32_e32 v152, v150, v201, vcc
	v_cndmask_b32_e32 v150, v201, v150, vcc
	ds_bpermute_b32 v153, v95, v150
	s_waitcnt lgkmcnt(8)
	v_pk_fma_f32 v[150:151], v[64:65], v[126:127], 0 op_sel_hi:[1,1,0]
	v_pk_fma_f32 v[126:127], v[30:31], v[126:127], 0 op_sel_hi:[1,1,0]
	v_pk_fma_f32 v[150:151], v[62:63], v[128:129], v[150:151]
	v_pk_fma_f32 v[126:127], v[32:33], v[128:129], v[126:127]
	s_waitcnt lgkmcnt(7)
	v_pk_fma_f32 v[128:129], v[68:69], v[130:131], v[150:151]
	v_pk_fma_f32 v[126:127], v[26:27], v[130:131], v[126:127]
	v_pk_fma_f32 v[128:129], v[66:67], v[132:133], v[128:129]
	v_pk_fma_f32 v[126:127], v[28:29], v[132:133], v[126:127]
	s_waitcnt lgkmcnt(6)
	v_pk_fma_f32 v[128:129], v[72:73], v[134:135], v[128:129]
	v_pk_fma_f32 v[126:127], v[22:23], v[134:135], v[126:127]
	v_pk_fma_f32 v[128:129], v[70:71], v[136:137], v[128:129]
	v_pk_fma_f32 v[126:127], v[24:25], v[136:137], v[126:127]
	s_waitcnt lgkmcnt(5)
	v_pk_fma_f32 v[128:129], v[50:51], v[118:119], v[128:129]
	v_pk_fma_f32 v[118:119], v[18:19], v[118:119], v[126:127]
	v_pk_fma_f32 v[126:127], v[52:53], v[120:121], v[128:129]
	v_pk_fma_f32 v[118:119], v[20:21], v[120:121], v[118:119]
	v_and_b32_e32 v100, 16, v60
	s_waitcnt lgkmcnt(4)
	v_pk_fma_f32 v[120:121], v[46:47], v[138:139], v[126:127]
	v_pk_fma_f32 v[118:119], v[14:15], v[138:139], v[118:119]
	s_waitcnt lgkmcnt(0)
	v_add_f32_e32 v130, v152, v153
	v_cmp_eq_u32_e64 s[8:9], 0, v100
	v_pk_fma_f32 v[120:121], v[48:49], v[140:141], v[120:121]
	v_pk_fma_f32 v[118:119], v[16:17], v[140:141], v[118:119]
	v_cndmask_b32_e64 v100, v130, v174, s[8:9]
	v_cndmask_b32_e64 v130, v174, v130, s[8:9]
	v_pk_fma_f32 v[120:121], v[42:43], v[142:143], v[120:121]
	v_pk_fma_f32 v[118:119], v[76:77], v[142:143], v[118:119]
	ds_bpermute_b32 v130, v94, v130
	v_pk_fma_f32 v[120:121], v[44:45], v[144:145], v[120:121]
	v_pk_fma_f32 v[118:119], v[74:75], v[144:145], v[118:119]
	v_pk_fma_f32 v[120:121], v[38:39], v[146:147], v[120:121]
	v_pk_fma_f32 v[118:119], v[80:81], v[146:147], v[118:119]
	v_pk_fma_f32 v[120:121], v[40:41], v[148:149], v[120:121]
	v_pk_fma_f32 v[118:119], v[78:79], v[148:149], v[118:119]
	v_pk_fma_f32 v[120:121], v[34:35], v[122:123], v[120:121]
	v_pk_fma_f32 v[118:119], v[2:3], v[122:123], v[118:119]
	v_pk_fma_f32 v[120:121], v[36:37], v[124:125], v[120:121]
	v_pk_fma_f32 v[118:119], v[4:5], v[124:125], v[118:119]
	s_waitcnt lgkmcnt(0)
	v_add_f32_e32 v150, v100, v130
	v_add_f32_e32 v146, v120, v121
	v_add_f32_e32 v100, v118, v119
	ds_read_b128 v[118:121], v101
	ds_read_b128 v[122:125], v111
	ds_read_b128 v[126:129], v112
	ds_read_b128 v[130:133], v113
	ds_read_b128 v[134:137], v114
	ds_read_b128 v[112:115], v115
	ds_read_b128 v[138:141], v116
	ds_read_b128 v[142:145], v117
	s_waitcnt lgkmcnt(7)
	v_pk_fma_f32 v[116:117], v[64:65], v[118:119], 0 op_sel_hi:[1,1,0]
	v_pk_fma_f32 v[118:119], v[30:31], v[118:119], 0 op_sel_hi:[1,1,0]
	v_pk_fma_f32 v[116:117], v[62:63], v[120:121], v[116:117]
	v_pk_fma_f32 v[118:119], v[32:33], v[120:121], v[118:119]
	s_waitcnt lgkmcnt(6)
	v_pk_fma_f32 v[116:117], v[68:69], v[122:123], v[116:117]
	v_pk_fma_f32 v[118:119], v[26:27], v[122:123], v[118:119]
	v_pk_fma_f32 v[116:117], v[66:67], v[124:125], v[116:117]
	v_pk_fma_f32 v[118:119], v[28:29], v[124:125], v[118:119]
	s_waitcnt lgkmcnt(5)
	v_pk_fma_f32 v[116:117], v[72:73], v[126:127], v[116:117]
	v_pk_fma_f32 v[118:119], v[22:23], v[126:127], v[118:119]
	v_pk_fma_f32 v[116:117], v[70:71], v[128:129], v[116:117]
	v_pk_fma_f32 v[118:119], v[24:25], v[128:129], v[118:119]
	s_waitcnt lgkmcnt(4)
	v_pk_fma_f32 v[116:117], v[50:51], v[130:131], v[116:117]
	v_pk_fma_f32 v[118:119], v[18:19], v[130:131], v[118:119]
	v_pk_fma_f32 v[116:117], v[52:53], v[132:133], v[116:117]
	v_pk_fma_f32 v[118:119], v[20:21], v[132:133], v[118:119]
	v_cndmask_b32_e32 v111, v202, v146, vcc
	s_waitcnt lgkmcnt(3)
	v_pk_fma_f32 v[116:117], v[46:47], v[134:135], v[116:117]
	v_pk_fma_f32 v[118:119], v[14:15], v[134:135], v[118:119]
	ds_bpermute_b32 v111, v95, v111
	v_pk_fma_f32 v[116:117], v[48:49], v[136:137], v[116:117]
	v_pk_fma_f32 v[118:119], v[16:17], v[136:137], v[118:119]
	s_waitcnt lgkmcnt(3)
	v_pk_fma_f32 v[116:117], v[42:43], v[112:113], v[116:117]
	v_pk_fma_f32 v[112:113], v[76:77], v[112:113], v[118:119]
	v_pk_fma_f32 v[116:117], v[44:45], v[114:115], v[116:117]
	v_pk_fma_f32 v[112:113], v[74:75], v[114:115], v[112:113]
	s_waitcnt lgkmcnt(2)
	v_pk_fma_f32 v[114:115], v[38:39], v[138:139], v[116:117]
	v_pk_fma_f32 v[112:113], v[80:81], v[138:139], v[112:113]
	v_cndmask_b32_e32 v101, v146, v202, vcc
	v_pk_fma_f32 v[114:115], v[40:41], v[140:141], v[114:115]
	v_pk_fma_f32 v[112:113], v[78:79], v[140:141], v[112:113]
	s_waitcnt lgkmcnt(0)
	v_add_f32_e32 v101, v101, v111
	v_pk_fma_f32 v[114:115], v[34:35], v[142:143], v[114:115]
	v_pk_fma_f32 v[112:113], v[2:3], v[142:143], v[112:113]
	v_cndmask_b32_e64 v146, v101, v172, s[8:9]
	v_cndmask_b32_e64 v101, v172, v101, s[8:9]
	v_pk_fma_f32 v[114:115], v[36:37], v[144:145], v[114:115]
	v_pk_fma_f32 v[112:113], v[4:5], v[144:145], v[112:113]
	ds_bpermute_b32 v147, v94, v101
	v_add_f32_e32 v136, v114, v115
	v_add_f32_e32 v101, v112, v113
	ds_read_b128 v[112:115], v103
	ds_read_b128 v[116:119], v104
	ds_read_b128 v[120:123], v105
	ds_read_b128 v[124:127], v106
	ds_read_b128 v[104:107], v107
	ds_read_b128 v[128:131], v108
	ds_read_b128 v[132:135], v109
	ds_read_b128 v[108:111], v110
	s_waitcnt lgkmcnt(7)
	v_pk_fma_f32 v[64:65], v[64:65], v[112:113], 0 op_sel_hi:[1,1,0]
	v_pk_fma_f32 v[30:31], v[30:31], v[112:113], 0 op_sel_hi:[1,1,0]
	v_pk_fma_f32 v[62:63], v[62:63], v[114:115], v[64:65]
	v_pk_fma_f32 v[30:31], v[32:33], v[114:115], v[30:31]
	s_waitcnt lgkmcnt(6)
	v_pk_fma_f32 v[32:33], v[68:69], v[116:117], v[62:63]
	v_pk_fma_f32 v[26:27], v[26:27], v[116:117], v[30:31]
	v_pk_fma_f32 v[30:31], v[66:67], v[118:119], v[32:33]
	v_pk_fma_f32 v[26:27], v[28:29], v[118:119], v[26:27]
	s_waitcnt lgkmcnt(5)
	v_pk_fma_f32 v[28:29], v[72:73], v[120:121], v[30:31]
	v_pk_fma_f32 v[22:23], v[22:23], v[120:121], v[26:27]
	v_pk_fma_f32 v[26:27], v[70:71], v[122:123], v[28:29]
	v_pk_fma_f32 v[22:23], v[24:25], v[122:123], v[22:23]
	s_waitcnt lgkmcnt(4)
	v_pk_fma_f32 v[24:25], v[50:51], v[124:125], v[26:27]
	v_pk_fma_f32 v[18:19], v[18:19], v[124:125], v[22:23]
	v_pk_fma_f32 v[22:23], v[52:53], v[126:127], v[24:25]
	v_pk_fma_f32 v[18:19], v[20:21], v[126:127], v[18:19]
	s_waitcnt lgkmcnt(3)
	v_pk_fma_f32 v[20:21], v[46:47], v[104:105], v[22:23]
	v_pk_fma_f32 v[14:15], v[14:15], v[104:105], v[18:19]
	v_pk_fma_f32 v[18:19], v[48:49], v[106:107], v[20:21]
	v_pk_fma_f32 v[14:15], v[16:17], v[106:107], v[14:15]
	s_waitcnt lgkmcnt(2)
	v_pk_fma_f32 v[16:17], v[42:43], v[128:129], v[18:19]
	v_pk_fma_f32 v[14:15], v[76:77], v[128:129], v[14:15]
	v_pk_fma_f32 v[16:17], v[44:45], v[130:131], v[16:17]
	v_pk_fma_f32 v[14:15], v[74:75], v[130:131], v[14:15]
	s_waitcnt lgkmcnt(1)
	v_pk_fma_f32 v[16:17], v[38:39], v[132:133], v[16:17]
	v_pk_fma_f32 v[14:15], v[80:81], v[132:133], v[14:15]
	v_pk_fma_f32 v[16:17], v[40:41], v[134:135], v[16:17]
	v_pk_fma_f32 v[14:15], v[78:79], v[134:135], v[14:15]
	s_waitcnt lgkmcnt(0)
	v_pk_fma_f32 v[16:17], v[34:35], v[108:109], v[16:17]
	v_pk_fma_f32 v[2:3], v[2:3], v[108:109], v[14:15]
	v_cndmask_b32_e32 v103, v136, v203, vcc
	v_cndmask_b32_e32 v136, v203, v136, vcc
	v_pk_fma_f32 v[14:15], v[36:37], v[110:111], v[16:17]
	v_pk_fma_f32 v[2:3], v[4:5], v[110:111], v[2:3]
	ds_bpermute_b32 v136, v95, v136
	v_add_f32_e32 v5, v14, v15
	v_add_f32_e32 v4, v2, v3
	v_and_b32_e32 v102, 8, v60
	v_cndmask_b32_e32 v2, v204, v5, vcc
	ds_bpermute_b32 v3, v95, v2
	s_waitcnt lgkmcnt(1)
	v_add_f32_e32 v30, v103, v136
	v_cndmask_b32_e64 v28, v168, v30, s[8:9]
	v_cndmask_b32_e32 v5, v5, v204, vcc
	ds_bpermute_b32 v26, v94, v28
	s_waitcnt lgkmcnt(1)
	v_add_f32_e32 v15, v5, v3
	v_cndmask_b32_e64 v3, v158, v15, s[8:9]
	ds_bpermute_b32 v16, v94, v3
	v_cndmask_b32_e64 v14, v30, v168, s[8:9]
	s_waitcnt lgkmcnt(1)
	v_add_f32_e32 v14, v14, v26
	v_cmp_eq_u32_e64 s[10:11], 0, v102
	v_add_f32_e32 v2, v146, v147
	v_and_b32_e32 v17, 4, v60
	v_cndmask_b32_e64 v3, v14, v150, s[10:11]
	v_cndmask_b32_e64 v5, v150, v14, s[10:11]
	v_cndmask_b32_e64 v14, v15, v158, s[8:9]
	s_waitcnt lgkmcnt(0)
	v_add_f32_e32 v14, v14, v16
	v_cndmask_b32_e64 v15, v2, v14, s[10:11]
	ds_bpermute_b32 v5, v93, v5
	ds_bpermute_b32 v15, v93, v15
	v_cndmask_b32_e64 v2, v14, v2, s[10:11]
	v_cmp_eq_u32_e64 s[12:13], 0, v17
	v_lshlrev_b32_e32 v16, 2, v96
	s_waitcnt lgkmcnt(1)
	v_add_f32_e32 v3, v3, v5
	s_waitcnt lgkmcnt(0)
	v_add_f32_e32 v2, v2, v15
	v_cndmask_b32_e64 v14, v2, v3, s[12:13]
	v_cndmask_b32_e64 v2, v3, v2, s[12:13]
	ds_bpermute_b32 v2, v16, v2
	v_cndmask_b32_e64 v3, v55, v90, s[14:15]
	v_lshlrev_b32_e32 v5, 2, v3
	v_cmp_lt_i32_e64 s[14:15], v91, v86
	s_waitcnt lgkmcnt(0)
	v_add_f32_e32 v2, v14, v2
	ds_bpermute_b32 v3, v5, v2
	v_cndmask_b32_e64 v14, v55, v91, s[14:15]
	v_lshlrev_b32_e32 v15, 2, v14
	v_and_b32_e32 v14, 3, v60
	v_cmp_eq_u32_e64 s[14:15], 0, v14
	s_waitcnt lgkmcnt(0)
	v_add_f32_e32 v2, v2, v3
	ds_bpermute_b32 v3, v15, v2
	v_bfe_u32 v14, v60, 2, 4
	v_lshlrev_b32_e32 v60, 2, v14
	s_and_saveexec_b64 s[52:53], s[14:15]
	s_cbranch_execz .LBB0_86
	global_load_dword v17, v60, s[50:51]
	s_waitcnt lgkmcnt(0)
	v_add_f32_e32 v2, v2, v3
	v_cmp_lt_u32_e64 s[16:17], 7, v14
	s_waitcnt vmcnt(0)
	v_add_f32_e32 v17, v2, v17
	s_and_saveexec_b64 s[18:19], s[16:17]
	s_xor_b64 s[54:55], exec, s[18:19]
	s_cbranch_execz .LBB0_83
	v_mul_f32_e64 v2, |v17|, s66
	v_exp_f32_e32 v18, v2
	s_lshl_b64 s[16:17], s[40:41], 5
	s_add_u32 s16, s58, s16
	s_addc_u32 s17, s59, s17
	v_add_f32_e32 v18, 1.0, v18
	v_lshl_add_u64 v[2:3], s[16:17], 0, v[60:61]
	v_cmp_gt_f32_e64 s[16:17], s67, v18
	v_max_f32_e32 v17, v17, v17
	v_min_f32_e32 v17, 0, v17
	v_cndmask_b32_e64 v19, 0, 32, s[16:17]
	v_ldexp_f32 v18, v18, v19
	v_log_f32_e32 v18, v18
	v_lshl_add_u64 v[2:3], v[2:3], 0, s[38:39]
	v_mul_f32_e32 v19, 0x3f317217, v18
	v_fma_f32 v19, v18, s68, -v19
	v_fmac_f32_e32 v19, 0x3377d1cf, v18
	v_fmac_f32_e32 v19, 0x3f317217, v18
	v_cmp_lt_f32_e64 s[18:19], |v18|, s69
	s_nop 1
	v_cndmask_b32_e64 v18, v18, v19, s[18:19]
	v_cndmask_b32_e64 v19, 0, v92, s[16:17]
	v_sub_f32_e32 v18, v18, v19
	v_sub_f32_e32 v17, v17, v18
